# v20: selected loop waits for the next-tile prefetch at the LDS store instead of at the loop top
# baseline (speedup 1.0000x reference)
.Lnsa2_skipfill:
	v_readfirstlane_b32 s92, v200
	s_lshr_b32 s92, s92, 8
	s_and_b32 s92, s92, 1
	s_mul_i32 s93, s92, 0xb00
	s_add_i32 s93, s93, 0x1d000
	s_add_i32 s92, s93, 148
	s_add_i32 s94, s93, 276
	s_add_i32 s95, s93, 192
	s_add_i32 s96, s93, 320
	s_xor_b64 s[50:51], s[2:3], -1
	s_and_b64 s[0:1], s[2:3], exec
	s_cselect_b32 s61, s82, s80
	s_lshl_b32 s60, s61, 8
	v_and_b32_e32 v181, 0xc0, v2
	v_and_b32_e32 v151, 31, v2
	v_or_b32_e32 v182, s60, v181
	v_ashrrev_i32_e32 v3, 8, v2
	v_or_b32_e32 v0, v182, v151
	v_add_u32_e32 v185, s81, v3
	v_lshl_add_u64 v[146:147], s[34:35], 0, v[0:1]
	v_mad_u64_u32 v[4:5], s[0:1], v146, s73, v[138:139]
	v_lshlrev_b32_e32 v152, 6, v185
	v_bfe_u32 v186, v2, 5, 1
	v_mad_i32_i24 v5, v147, s73, v5
	v_ashrrev_i32_e32 v153, 31, v152
	v_ashrrev_i32_e32 v183, 3, v2
	v_lshl_add_u64 v[4:5], v[152:153], 1, v[4:5]
	v_lshlrev_b32_e32 v0, 4, v186
	v_med3_i32 v36, v183, 0, v141
	v_lshlrev_b32_e32 v38, 3, v2
	v_lshl_add_u64 v[24:25], v[4:5], 0, v[0:1]
	v_mul_u32_u24_e32 v36, 0x600, v36
	v_mov_b32_e32 v37, v1
	v_and_b32_e32 v150, 56, v38
	v_add_co_u32_e32 v28, vcc, s74, v24
	v_lshl_add_u64 v[36:37], v[36:37], 1, s[44:45]
	v_lshlrev_b32_e32 v44, 1, v150
	v_mov_b32_e32 v45, v1
	v_lshl_add_u64 v[32:33], v[24:25], 0, s[20:21]
	v_addc_co_u32_e32 v29, vcc, 0, v25, vcc
	v_lshl_add_u64 v[40:41], v[36:37], 0, v[44:45]
	global_load_dwordx4 v[4:7], v[24:25], off
	global_load_dwordx4 v[8:11], v[24:25], off offset:32
	global_load_dwordx4 v[12:15], v[32:33], off offset:32
	global_load_dwordx4 v[16:19], v[32:33], off offset:64
	global_load_dwordx4 v[20:23], v[24:25], off offset:64
	s_nop 0
	global_load_dwordx4 v[24:27], v[24:25], off offset:96
	s_nop 0
	global_load_dwordx4 v[28:31], v[28:29], off
	s_nop 0
	global_load_dwordx4 v[32:35], v[32:33], off offset:96
	s_nop 0
	global_load_dwordx4 v[36:39], v[40:41], off offset:1792
	s_nop 0
	global_load_dwordx4 v[40:43], v[40:41], off offset:1920
	v_or_b32_e32 v148, 32, v146
	v_mov_b32_e32 v149, v147
	v_lshl_add_u64 v[46:47], v[146:147], 2, s[18:19]
	v_lshl_add_u64 v[48:49], v[148:149], 2, s[18:19]
	global_load_dword v187, v[46:47], off
	global_load_dword v188, v[48:49], off
	v_lshlrev_b32_e32 v47, 7, v2
	v_and_b32_e32 v46, 63, v2
	v_lshlrev_b32_e32 v48, 4, v2
	v_mad_i32_i24 v175, v3, s72, 0
	v_and_b32_e32 v3, 0xffffe000, v47
	v_lshlrev_b32_e32 v46, 4, v46
	v_mul_lo_u32 v47, v183, s75
	v_and_b32_e32 v48, 0x70, v48
	v_add_u32_e32 v3, 0, v3
	v_and_b32_e32 v49, 16, v2
	v_lshrrev_b32_e32 v50, 2, v2
	v_mul_u32_u24_e32 v51, 0x90, v151
	v_add3_u32 v140, 0, v47, v48
	v_add_u32_e32 v176, v3, v46
	v_lshlrev_b32_e32 v184, 2, v186
	v_lshlrev_b32_e32 v3, 2, v2
	v_mad_u64_u32 v[142:143], s[0:1], v183, 48, v[140:141]
	v_add3_u32 v178, 0, v51, v0
	v_and_or_b32 v0, v50, 3, v184
	v_and_or_b32 v3, v3, 12, v49
	v_mul_u32_u24_e32 v0, 0xc0, v0
	v_lshlrev_b32_e32 v3, 1, v3
	v_add3_u32 v179, 0, v0, v3
	v_bitop3_b32 v0, v2, 31, v170 bitop3:0xe0
	s_lshl_b32 s84, s61, 2
	v_lshl_add_u64 v[144:145], s[44:45], 0, v[44:45]
	v_mad_u64_u32 v[154:155], s[0:1], v146, s73, 0
	v_sub_u32_e32 v192, v0, v184
	v_mov_b32_e32 v0, v1
	v_mov_b32_e32 v2, v1
	v_mov_b32_e32 v3, v1
	s_mov_b32 s85, 0
	s_add_i32 s83, s84, 4
	v_or_b32_e32 v143, 31, v182
	v_or_b32_e32 v177, 63, v182
	v_mad_i32_i24 v155, v147, s73, v155
	v_add_u32_e32 v190, 0xffffff41, v182
	v_add_u32_e32 v191, 0xffffff61, v182
	v_add_u32_e32 v180, 64, v183
	s_add_i32 s86, s60, 0x100
	v_mov_b32_e32 v193, 0xf149f2ca
	v_mov_b32_e32 v194, 0xf149f2ca
	s_mov_b32 s87, 0
	s_mov_b32 s0, 0
	v_mov_b64_e32 v[156:157], v[0:1]
	s_waitcnt vmcnt(11)
	ds_write_b128 v176, v[4:7] offset:53248
	s_waitcnt vmcnt(10)
	ds_write_b128 v176, v[8:11] offset:54272
	s_waitcnt vmcnt(7)
	ds_write_b128 v176, v[20:23] offset:55296
	s_waitcnt vmcnt(6)
	ds_write_b128 v176, v[24:27] offset:56320
	s_waitcnt vmcnt(5)
	ds_write_b128 v176, v[28:31] offset:57344
	ds_write_b128 v176, v[12:15] offset:58368
	ds_write_b128 v176, v[16:19] offset:59392
	s_waitcnt vmcnt(4)
	ds_write_b128 v176, v[32:35] offset:60416
	s_waitcnt lgkmcnt(0)
	s_barrier
	s_waitcnt vmcnt(3)
	ds_write_b128 v140, v[36:39]
	s_waitcnt vmcnt(2)
	ds_write_b128 v142, v[40:43] offset:18432
	s_waitcnt vmcnt(0) lgkmcnt(0)
	s_barrier
	ds_read_b32 v189, v175 offset:43524
	v_mov_b32_e32 v16, v1
	v_mov_b32_e32 v17, v1
	v_mov_b32_e32 v4, v1
	v_mov_b32_e32 v5, v1
	v_mov_b32_e32 v6, v1
	v_mov_b32_e32 v7, v1
	v_mov_b32_e32 v8, v1
	v_mov_b32_e32 v9, v1
	v_mov_b32_e32 v10, v1
	v_mov_b32_e32 v11, v1
	v_mov_b32_e32 v12, v1
	v_mov_b32_e32 v13, v1
	v_mov_b32_e32 v14, v1
	v_mov_b32_e32 v15, v1
	v_mov_b64_e32 v[48:49], v[16:17]
	v_mov_b64_e32 v[64:65], v[16:17]
	v_mov_b64_e32 v[32:33], v[16:17]
	v_mov_b64_e32 v[46:47], v[14:15]
	v_mov_b64_e32 v[44:45], v[12:13]
	v_mov_b64_e32 v[42:43], v[10:11]
	v_mov_b64_e32 v[40:41], v[8:9]
	v_mov_b64_e32 v[38:39], v[6:7]
	v_mov_b64_e32 v[36:37], v[4:5]
	v_mov_b64_e32 v[34:35], v[2:3]
	v_mov_b64_e32 v[62:63], v[14:15]
	v_mov_b64_e32 v[60:61], v[12:13]
	v_mov_b64_e32 v[58:59], v[10:11]
	v_mov_b64_e32 v[56:57], v[8:9]
	v_mov_b64_e32 v[54:55], v[6:7]
	v_mov_b64_e32 v[52:53], v[4:5]
	v_mov_b64_e32 v[50:51], v[2:3]
	v_mov_b64_e32 v[30:31], v[14:15]
	v_mov_b64_e32 v[28:29], v[12:13]
	v_mov_b64_e32 v[26:27], v[10:11]
	v_mov_b64_e32 v[24:25], v[8:9]
	v_mov_b64_e32 v[22:23], v[6:7]
	v_mov_b64_e32 v[20:21], v[4:5]
	v_mov_b64_e32 v[18:19], v[2:3]

.LBB0_634:
	s_lshl_b32 s0, 1, s0
	s_nop 0
	v_and_b32_e32 v0, s0, v187
	v_and_b32_e32 v66, s0, v188
	v_cmp_ne_u32_e64 s[6:7], 0, v0
	v_cmp_ne_u32_e32 vcc, 0, v66
	v_cmp_le_u32_e64 s[8:9], s85, v143
	v_cmp_le_u32_e64 s[2:3], s85, v177
	s_and_b64 s[8:9], s[8:9], s[6:7]
	s_and_b64 s[2:3], s[2:3], vcc
	s_cmp_lg_u64 s[8:9], 0
	s_cselect_b64 s[8:9], -1, 0
	s_cmp_lg_u64 s[2:3], 0
	s_cselect_b64 s[2:3], -1, 0
	v_cndmask_b32_e64 v0, 0, 1, s[8:9]
	v_cndmask_b32_e64 v167, 0, 1, s[2:3]
	s_or_b64 s[0:1], s[8:9], s[2:3]
	s_and_saveexec_b64 s[54:55], s[0:1]
	s_cbranch_execz .LBB0_646
	s_cmp_eq_u32 s87, 0
	s_cselect_b64 s[58:59], -1, 0
	s_and_b64 s[0:1], s[58:59], exec
	s_cselect_b32 s0, 0, 0x2400
	v_add_u32_e32 v168, s0, v178
	ds_read_b128 v[158:161], v168
	ds_read_b128 v[162:165], v176 offset:53248
	v_cmp_gt_i32_e64 s[4:5], s85, v190
	s_waitcnt lgkmcnt(2)
	v_cndmask_b32_e64 v66, v173, v189, s[6:7]
	ds_read_b128 v[196:199], v168 offset:32
	ds_read_b128 v[202:205], v176 offset:54272
	ds_read_b128 v[206:209], v176 offset:57344
	ds_read_b128 v[210:213], v176 offset:58368
	v_cndmask_b32_e64 v166, 0, v171, s[4:5]
	v_cndmask_b32_e64 v66, v66, 0, s[4:5]
	v_cndmask_b32_e32 v67, v173, v189, vcc
	v_cmp_gt_i32_e64 s[4:5], s85, v191
	v_cndmask_b32_e64 v240, v173, v66, s[8:9]
	s_nop 0
	v_cndmask_b32_e64 v67, v67, 0, s[4:5]
	s_nop 1
	v_cndmask_b32_e64 v241, v173, v67, s[2:3]
	s_waitcnt lgkmcnt(4)
	v_mfma_f32_32x32x16_bf16 v[98:113], v[158:161], v[162:165], 0
	s_waitcnt lgkmcnt(1)
	v_mfma_f32_32x32x16_bf16 v[114:129], v[158:161], v[206:209], 0
	ds_read_b128 v[158:161], v168 offset:4608
	ds_read_b128 v[214:217], v168 offset:4640
	s_waitcnt lgkmcnt(1)
	v_mfma_f32_32x32x16_bf16 v[82:97], v[158:161], v[162:165], 0
	v_mfma_f32_32x32x16_bf16 v[66:81], v[158:161], v[206:209], 0
	v_mfma_f32_32x32x16_bf16 v[98:113], v[196:199], v[202:205], v[98:113]
	v_mfma_f32_32x32x16_bf16 v[114:129], v[196:199], v[210:213], v[114:129]
	ds_read_b128 v[158:161], v168 offset:64
	ds_read_b128 v[162:165], v176 offset:55296
	ds_read_b128 v[196:199], v168 offset:96
	ds_read_b128 v[206:209], v176 offset:56320
	s_waitcnt lgkmcnt(4)
	v_mfma_f32_32x32x16_bf16 v[82:97], v[214:217], v[202:205], v[82:97]
	v_mfma_f32_32x32x16_bf16 v[66:81], v[214:217], v[210:213], v[66:81]
	ds_read_b128 v[202:205], v176 offset:59392
	ds_read_b128 v[210:213], v176 offset:60416
	s_waitcnt lgkmcnt(4)
	v_mfma_f32_32x32x16_bf16 v[98:113], v[158:161], v[162:165], v[98:113]
	s_waitcnt lgkmcnt(1)
	v_mfma_f32_32x32x16_bf16 v[114:129], v[158:161], v[202:205], v[114:129]
	ds_read_b128 v[158:161], v168 offset:4672
	ds_read_b128 v[214:217], v168 offset:4704
	s_waitcnt lgkmcnt(1)
	v_mfma_f32_32x32x16_bf16 v[82:97], v[158:161], v[162:165], v[82:97]
	v_mfma_f32_32x32x16_bf16 v[66:81], v[158:161], v[202:205], v[66:81]
	v_cndmask_b32_e64 v158, 0, v172, s[6:7]
	v_or3_b32 v0, v158, v166, v0
	v_cndmask_b32_e64 v158, v158, v0, s[8:9]
	v_and_b32_e32 v0, 0x100, v158
	v_cmp_ne_u32_e64 s[6:7], 0, v0
	v_add_u32_e32 v0, s60, v192
	v_mfma_f32_32x32x16_bf16 v[98:113], v[196:199], v[206:209], v[98:113]
	v_mfma_f32_32x32x16_bf16 v[114:129], v[196:199], v[210:213], v[114:129]
	s_waitcnt lgkmcnt(0)
	v_mfma_f32_32x32x16_bf16 v[82:97], v[214:217], v[206:209], v[82:97]
	v_mfma_f32_32x32x16_bf16 v[66:81], v[214:217], v[210:213], v[66:81]
	s_and_saveexec_b64 s[8:9], s[6:7]
	s_cbranch_execz .LBB0_641
	v_lshl_add_u32 v206, v0, 2, s92
	v_and_b32_e32 v205, 0x10000, v158
	v_cmp_ne_u32_e64 s[6:7], 0, v205
	v_mov_b32_e32 v207, s93
	s_nop 1
	v_cndmask_b32_e64 v206, v207, v206, s[6:7]
	ds_read2_b32 v[208:209], v206 offset0:59 offset1:58
	ds_read2_b32 v[210:211], v206 offset0:57 offset1:56
	ds_read2_b32 v[212:213], v206 offset0:51 offset1:50
	ds_read2_b32 v[214:215], v206 offset0:49 offset1:48
	ds_read2_b32 v[216:217], v206 offset0:43 offset1:42
	ds_read2_b32 v[218:219], v206 offset0:41 offset1:40
	ds_read2_b32 v[220:221], v206 offset0:35 offset1:34
	ds_read2_b32 v[222:223], v206 offset0:33 offset1:32
	ds_read2_b32 v[224:225], v206 offset0:27 offset1:26
	ds_read2_b32 v[226:227], v206 offset0:25 offset1:24
	ds_read2_b32 v[228:229], v206 offset0:19 offset1:18
	ds_read2_b32 v[230:231], v206 offset0:17 offset1:16
	ds_read2_b32 v[232:233], v206 offset0:11 offset1:10
	ds_read2_b32 v[234:235], v206 offset0:9 offset1:8
	ds_read2_b32 v[236:237], v206 offset0:3 offset1:2
	ds_read2_b32 v[238:239], v206 offset0:1 offset1:0
	s_waitcnt lgkmcnt(8)
	v_pk_add_f32 v[98:99], v[98:99], v[208:209]
	v_pk_add_f32 v[100:101], v[100:101], v[210:211]
	v_pk_add_f32 v[102:103], v[102:103], v[212:213]
	v_pk_add_f32 v[104:105], v[104:105], v[214:215]
	v_pk_add_f32 v[106:107], v[106:107], v[216:217]
	v_pk_add_f32 v[108:109], v[108:109], v[218:219]
	v_pk_add_f32 v[110:111], v[110:111], v[220:221]
	v_pk_add_f32 v[112:113], v[112:113], v[222:223]
	s_waitcnt lgkmcnt(0)
	v_pk_add_f32 v[82:83], v[82:83], v[224:225]
	v_pk_add_f32 v[84:85], v[84:85], v[226:227]
	v_pk_add_f32 v[86:87], v[86:87], v[228:229]
	v_pk_add_f32 v[88:89], v[88:89], v[230:231]
	v_pk_add_f32 v[90:91], v[90:91], v[232:233]
	v_pk_add_f32 v[92:93], v[92:93], v[234:235]
	v_pk_add_f32 v[94:95], v[94:95], v[236:237]
	v_pk_add_f32 v[96:97], v[96:97], v[238:239]

.LBB0_646:
	s_or_b64 exec, exec, s[54:55]
	s_andn2_b64 vcc, exec, s[10:11]
	s_cbranch_vccnz .LBB0_648
	s_cmp_eq_u32 s87, 0
	s_cselect_b32 s0, 0x2400, 0
	v_add_u32_e32 v0, s0, v140
	s_cselect_b32 s0, 0x7800, s78
	v_add_u32_e32 v66, s0, v142
	s_waitcnt vmcnt(0)
	ds_write_b128 v0, v[130:133]
	ds_write_b128 v66, v[134:137]
